# row loops + attention epilogues + tr_item burst + w_mq fast path; stores drained before grid.sync
# baseline (speedup 1.0000x reference)
; __device__ __forceinline__ unsigned cvtpk(float lo, float hi) { f32x2_t v = {lo, hi}; bf16x2_t b = __builtin_convertvector(v, bf16x2_t); return __builtin_bit_cast(unsigned, b); }
; #define NTL(p) __builtin_nontemporal_load(&(p))
; __device__ __forceinline__ void rms_row_bf16(const float* xrow, const float* g, bf16_t* orow, int lane) {
;     const f32x4* xr = (const f32x4*)xrow + lane;
;     f32x4 v[8]; float s = 0.f;
; #pragma unroll
;     for (int j = 0; j < 8; ++j) { v[j] = NTL(xr[64 * j]); s += (v[j].x * v[j].x + v[j].y * v[j].y) + (v[j].z * v[j].z + v[j].w * v[j].w); }
;     const float r = 1.0f / sqrtf(wave_sum(s) * (1.0f / DM) + EPS);
;     const f32x4* gr = (const f32x4*)g + lane;
;     u32x2* o8 = (u32x2*)orow + lane;
; #pragma unroll
;     for (int j = 0; j < 8; ++j) { const f32x4 gv = gr[64 * j]; u32x2 w; w.x = cvtpk(v[j].x * r * gv.x, v[j].y * r * gv.y); w.y = cvtpk(v[j].z * r * gv.z, v[j].w * r * gv.w); o8[64 * j] = w; }
; }
; template <int PART>
; __device__ __forceinline__ void prologue(const Params& p, LAS unsigned char* lds, int G, int blk) {
;     ...
;     for (int m = gw; m < MT; m += NGW) rms_row_bf16(p.x + (size_t)m * DM, p.g_mix_pre, H + (size_t)m * DM, lane);
.Lrow_prox_compB:
	v_pk_mul_f32 v[28:29], v[120:121], v[120:121]
	v_pk_mul_f32 v[36:37], v[122:123], v[122:123]
	v_pk_fma_f32 v[28:29], v[124:125], v[124:125], v[28:29]
	v_pk_fma_f32 v[36:37], v[126:127], v[126:127], v[36:37]
	v_pk_fma_f32 v[28:29], v[132:133], v[132:133], v[28:29]
	v_pk_fma_f32 v[36:37], v[134:135], v[134:135], v[36:37]
	v_pk_fma_f32 v[28:29], v[136:137], v[136:137], v[28:29]
	v_pk_fma_f32 v[36:37], v[138:139], v[138:139], v[36:37]
	v_pk_fma_f32 v[28:29], v[140:141], v[140:141], v[28:29]
	v_pk_fma_f32 v[36:37], v[142:143], v[142:143], v[36:37]
	v_pk_fma_f32 v[28:29], v[144:145], v[144:145], v[28:29]
	v_pk_fma_f32 v[36:37], v[146:147], v[146:147], v[36:37]
	v_pk_fma_f32 v[28:29], v[148:149], v[148:149], v[28:29]
	v_pk_fma_f32 v[36:37], v[150:151], v[150:151], v[36:37]
	v_pk_fma_f32 v[28:29], v[152:153], v[152:153], v[28:29]
	v_pk_fma_f32 v[36:37], v[154:155], v[154:155], v[36:37]
	v_pk_add_f32 v[28:29], v[28:29], v[36:37]
	s_nop 0
	v_add_f32_e32 v11, v28, v29
	ds_bpermute_b32 v42, v5, v11
	s_waitcnt lgkmcnt(0)
	v_add_f32_e32 v11, v11, v42
	ds_bpermute_b32 v42, v6, v11
	s_waitcnt lgkmcnt(0)
	v_add_f32_e32 v11, v11, v42
	ds_bpermute_b32 v42, v7, v11
	s_waitcnt lgkmcnt(0)
	v_add_f32_e32 v11, v11, v42
	ds_bpermute_b32 v42, v8, v11
	s_waitcnt lgkmcnt(0)
	v_add_f32_e32 v11, v11, v42
	ds_bpermute_b32 v42, v9, v11
	s_waitcnt lgkmcnt(0)
	v_add_f32_e32 v11, v11, v42
	ds_bpermute_b32 v42, v10, v11
	s_waitcnt lgkmcnt(0)
	v_add_f32_e32 v11, v11, v42
	v_fmamk_f32 v11, v11, 0x3a000000, v3
	v_mul_f32_e32 v43, 0x4f800000, v11
	v_cmp_gt_f32_e32 vcc, s85, v11
	s_nop 1
	v_cndmask_b32_e32 v11, v11, v43, vcc
	v_sqrt_f32_e32 v43, v11
	s_nop 0
	v_add_u32_e32 v92, -1, v43
	v_add_u32_e32 v129, 1, v43
	v_fma_f32 v161, -v92, v43, v11
	v_fma_f32 v42, -v129, v43, v11
	v_cmp_ge_f32_e64 s[80:81], 0, v161
	s_nop 1
	v_cndmask_b32_e64 v43, v43, v92, s[80:81]
	v_cmp_lt_f32_e64 s[80:81], 0, v42
	s_nop 1
	v_cndmask_b32_e64 v43, v43, v129, s[80:81]
	v_mul_f32_e32 v92, 0x37800000, v43
	v_cndmask_b32_e32 v43, v43, v92, vcc
	v_cmp_class_f32_e32 vcc, v11, v4
	s_nop 1
	v_cndmask_b32_e32 v11, v43, v11, vcc
	v_div_scale_f32 v43, s[80:81], v11, v11, 1.0
	v_rcp_f32_e32 v129, v43
	v_div_scale_f32 v92, vcc, 1.0, v11, 1.0
	v_fma_f32 v161, -v43, v129, 1.0
	v_fmac_f32_e32 v129, v161, v129
	v_mul_f32_e32 v161, v92, v129
	v_fma_f32 v42, -v43, v161, v92
	v_fmac_f32_e32 v161, v42, v129
	v_fma_f32 v43, -v43, v161, v92
	v_div_fmas_f32 v43, v43, v129, v161
	v_div_fixup_f32 v44, v43, v11, 1.0
	v_pk_mul_f32 v[130:131], v[120:121], v[44:45] op_sel_hi:[1,0]
	v_pk_mul_f32 v[156:157], v[122:123], v[44:45] op_sel_hi:[1,0]
	v_pk_mul_f32 v[130:131], v[12:13], v[130:131]
	v_pk_mul_f32 v[156:157], v[14:15], v[156:157]
	v_cvt_pk_bf16_f32 v158, v130, v131
	v_cvt_pk_bf16_f32 v159, v156, v157
	global_store_dwordx2 v1, v[158:159], s[78:79] offset:0
	v_pk_mul_f32 v[130:131], v[124:125], v[44:45] op_sel_hi:[1,0]
	v_pk_mul_f32 v[156:157], v[126:127], v[44:45] op_sel_hi:[1,0]
	v_pk_mul_f32 v[130:131], v[16:17], v[130:131]
	v_pk_mul_f32 v[156:157], v[18:19], v[156:157]
	v_cvt_pk_bf16_f32 v166, v130, v131
	v_cvt_pk_bf16_f32 v167, v156, v157
	global_store_dwordx2 v1, v[166:167], s[78:79] offset:512
	v_pk_mul_f32 v[130:131], v[132:133], v[44:45] op_sel_hi:[1,0]
	v_pk_mul_f32 v[156:157], v[134:135], v[44:45] op_sel_hi:[1,0]
	v_pk_mul_f32 v[130:131], v[20:21], v[130:131]
	v_pk_mul_f32 v[156:157], v[22:23], v[156:157]
	v_cvt_pk_bf16_f32 v168, v130, v131
	v_cvt_pk_bf16_f32 v169, v156, v157
	global_store_dwordx2 v1, v[168:169], s[78:79] offset:1024
	v_pk_mul_f32 v[130:131], v[136:137], v[44:45] op_sel_hi:[1,0]
	v_pk_mul_f32 v[156:157], v[138:139], v[44:45] op_sel_hi:[1,0]
	v_pk_mul_f32 v[130:131], v[24:25], v[130:131]
	v_pk_mul_f32 v[156:157], v[26:27], v[156:157]
	v_cvt_pk_bf16_f32 v170, v130, v131
	v_cvt_pk_bf16_f32 v171, v156, v157
	global_store_dwordx2 v1, v[170:171], s[78:79] offset:1536
	v_pk_mul_f32 v[130:131], v[140:141], v[44:45] op_sel_hi:[1,0]
	v_pk_mul_f32 v[156:157], v[142:143], v[44:45] op_sel_hi:[1,0]
	v_pk_mul_f32 v[130:131], v[52:53], v[130:131]
	v_pk_mul_f32 v[156:157], v[54:55], v[156:157]
	v_cvt_pk_bf16_f32 v158, v130, v131
	v_cvt_pk_bf16_f32 v159, v156, v157
	global_store_dwordx2 v1, v[158:159], s[78:79] offset:2048
	v_pk_mul_f32 v[130:131], v[144:145], v[44:45] op_sel_hi:[1,0]
	v_pk_mul_f32 v[156:157], v[146:147], v[44:45] op_sel_hi:[1,0]
	v_pk_mul_f32 v[130:131], v[56:57], v[130:131]
	v_pk_mul_f32 v[156:157], v[58:59], v[156:157]
	v_cvt_pk_bf16_f32 v166, v130, v131
	v_cvt_pk_bf16_f32 v167, v156, v157
	global_store_dwordx2 v1, v[166:167], s[78:79] offset:2560
	v_pk_mul_f32 v[130:131], v[148:149], v[44:45] op_sel_hi:[1,0]
	v_pk_mul_f32 v[156:157], v[150:151], v[44:45] op_sel_hi:[1,0]
	v_pk_mul_f32 v[130:131], v[60:61], v[130:131]
	v_pk_mul_f32 v[156:157], v[62:63], v[156:157]
	v_cvt_pk_bf16_f32 v168, v130, v131
	v_cvt_pk_bf16_f32 v169, v156, v157
	global_store_dwordx2 v1, v[168:169], s[78:79] offset:3072
	v_pk_mul_f32 v[130:131], v[152:153], v[44:45] op_sel_hi:[1,0]
	v_pk_mul_f32 v[156:157], v[154:155], v[44:45] op_sel_hi:[1,0]
	v_pk_mul_f32 v[130:131], v[64:65], v[130:131]
	v_pk_mul_f32 v[156:157], v[66:67], v[156:157]
	v_cvt_pk_bf16_f32 v170, v130, v131
	v_cvt_pk_bf16_f32 v171, v156, v157
	global_store_dwordx2 v1, v[170:171], s[78:79] offset:3584
	s_add_u32 s78, s78, s62
	s_addc_u32 s79, s79, 0
	s_mov_b32 s12, s84
	s_cmp_lt_u32 s12, 0x8000
	s_cbranch_scc1 .Lrow_prox_top
; template <int PART>
; __device__ __forceinline__ void prologue(const Params& p, LAS unsigned char* lds, int G, int blk) {
;     ...
;     for (int m = gw; m < MT; m += NGW) rms_row_bf16(p.x + (size_t)m * DM, p.g_mix_pre, H + (size_t)m * DM, lane);
;     for (int m = gw; m < NB * 256; m += NGW) rms_row_bf16(p.mem + (size_t)m * DM, p.g_mem_kv, memn + (size_t)m * DM, lane);
.Lrow_prox_done:
	s_waitcnt vmcnt(0)
.LBB0_51:
	s_cmpk_gt_i32 s20, 0x7ff
	v_readlane_b32 s58, v245, 2
	v_readlane_b32 s59, v245, 3
	s_cbranch_scc1 .LBB0_54
	v_mbcnt_hi_u32_b32 v2, -1, v190
	v_and_b32_e32 v1, 64, v2
	v_add_u32_e32 v3, 64, v1
	v_xor_b32_e32 v1, 1, v2
	v_cmp_lt_i32_e32 vcc, v1, v3
	v_xor_b32_e32 v4, 2, v2
	v_readlane_b32 s68, v245, 8
	v_cndmask_b32_e32 v1, v2, v1, vcc
	v_cmp_lt_i32_e32 vcc, v4, v3
	v_mov_b32_e32 v161, 0
	v_readlane_b32 s69, v245, 9
	v_cndmask_b32_e32 v4, v2, v4, vcc
	v_lshlrev_b32_e32 v36, 2, v4
	v_xor_b32_e32 v4, 4, v2
	v_cmp_lt_i32_e32 vcc, v4, v3
	v_lshl_add_u64 v[22:23], s[68:69], 0, v[160:161]
	s_mov_b64 s[4:5], 0x1400
	v_cndmask_b32_e32 v4, v2, v4, vcc
	v_lshlrev_b32_e32 v37, 2, v4
	v_xor_b32_e32 v4, 8, v2
	v_lshl_add_u64 v[26:27], v[22:23], 0, s[4:5]
	s_mov_b64 s[4:5], 0x1800
	v_cmp_lt_i32_e32 vcc, v4, v3
	v_lshl_add_u64 v[28:29], v[22:23], 0, s[4:5]
	s_mov_b64 s[4:5], 0x1c00
	v_cndmask_b32_e32 v4, v2, v4, vcc
	v_lshl_add_u64 v[32:33], v[22:23], 0, s[4:5]
	v_readlane_b32 s4, v245, 1
	v_lshlrev_b32_e32 v38, 2, v4
	v_xor_b32_e32 v4, 16, v2
	s_ashr_i32 s3, s4, 31
	v_cmp_lt_i32_e32 vcc, v4, v3
	s_add_u32 s12, s21, s4
	s_addc_u32 s13, 0, s3
	v_cndmask_b32_e32 v4, v2, v4, vcc
	v_lshlrev_b32_e32 v39, 2, v4
	v_xor_b32_e32 v4, 32, v2
	s_lshl_b64 s[4:5], s[12:13], 13
	v_cmp_lt_i32_e32 vcc, v4, v3
	s_add_u32 s4, s38, s4
	s_addc_u32 s5, s39, s5
	v_cndmask_b32_e32 v2, v2, v4, vcc
	v_lshlrev_b32_e32 v40, 2, v2
	s_mov_b64 s[0:1], 0x1000
	v_lshl_add_u64 v[2:3], s[4:5], 0, v[160:161]
	s_ashr_i32 s95, s94, 31
	v_lshl_add_u64 v[24:25], v[22:23], 0, s[0:1]
	v_lshl_add_u64 v[34:35], v[2:3], 0, s[0:1]
	s_lshl_b64 s[4:5], s[94:95], 13
	s_lshl_b64 s[0:1], s[12:13], 12
	s_add_u32 s0, s28, s0
	v_mov_b32_e32 v31, v161
	s_addc_u32 s1, s29, s1
	v_lshl_add_u64 v[2:3], s[0:1], 0, v[30:31]
	s_mov_b64 s[0:1], 0x8400800
	v_lshlrev_b32_e32 v1, 2, v1
	v_lshl_add_u64 v[30:31], v[2:3], 0, s[0:1]
	s_lshl_b64 s[12:13], s[94:95], 12
	v_mov_b32_e32 v41, 0x358637bd
	s_mov_b32 s3, 0xf800000
	v_mov_b32_e32 v42, 0x260
	v_readlane_b32 s70, v245, 10
	v_readlane_b32 s71, v245, 11
	v_readlane_b32 s72, v245, 12
	v_readlane_b32 s73, v245, 13
	v_readlane_b32 s74, v245, 14
	v_readlane_b32 s75, v245, 15
	v_readlane_b32 s76, v245, 16
	v_readlane_b32 s77, v245, 17
	v_readlane_b32 s78, v245, 18
	v_readlane_b32 s79, v245, 19
	v_readlane_b32 s80, v245, 20
	v_readlane_b32 s81, v245, 21
	v_readlane_b32 s82, v245, 22
	v_readlane_b32 s83, v245, 23

; __device__ __forceinline__ unsigned cvtpk(float lo, float hi) { f32x2_t v = {lo, hi}; bf16x2_t b = __builtin_convertvector(v, bf16x2_t); return __builtin_bit_cast(unsigned, b); }
; #define NTL(p) __builtin_nontemporal_load(&(p))
; __device__ __forceinline__ void rms_row_bf16(const float* xrow, const float* g, bf16_t* orow, int lane) {
;     const f32x4* xr = (const f32x4*)xrow + lane;
;     f32x4 v[8]; float s = 0.f;
; #pragma unroll
;     for (int j = 0; j < 8; ++j) { v[j] = NTL(xr[64 * j]); s += (v[j].x * v[j].x + v[j].y * v[j].y) + (v[j].z * v[j].z + v[j].w * v[j].w); }
;     const float r = 1.0f / sqrtf(wave_sum(s) * (1.0f / DM) + EPS);
;     const f32x4* gr = (const f32x4*)g + lane;
;     u32x2* o8 = (u32x2*)orow + lane;
; #pragma unroll
;     for (int j = 0; j < 8; ++j) { const f32x4 gv = gr[64 * j]; u32x2 w; w.x = cvtpk(v[j].x * r * gv.x, v[j].y * r * gv.y); w.y = cvtpk(v[j].z * r * gv.z, v[j].w * r * gv.w); o8[64 * j] = w; }
; }
; template <int PART>
; __device__ __forceinline__ void prologue(const Params& p, LAS unsigned char* lds, int G, int blk) {
;     ...
;     for (int m = gw; m < MT; m += NGW) rms_row_bf16(p.x + (size_t)m * DM, p.g_mix_pre, H + (size_t)m * DM, lane);
;     for (int m = gw; m < NB * 256; m += NGW) rms_row_bf16(p.mem + (size_t)m * DM, p.g_mem_kv, memn + (size_t)m * DM, lane);
.Lrow_prom_compB:
	v_pk_mul_f32 v[20:21], v[88:89], v[88:89]
	v_pk_mul_f32 v[36:37], v[90:91], v[90:91]
	v_pk_fma_f32 v[20:21], v[112:113], v[112:113], v[20:21]
	v_pk_fma_f32 v[36:37], v[114:115], v[114:115], v[36:37]
	v_pk_fma_f32 v[20:21], v[116:117], v[116:117], v[20:21]
	v_pk_fma_f32 v[36:37], v[118:119], v[118:119], v[36:37]
	v_pk_fma_f32 v[20:21], v[120:121], v[120:121], v[20:21]
	v_pk_fma_f32 v[36:37], v[122:123], v[122:123], v[36:37]
	v_pk_fma_f32 v[20:21], v[124:125], v[124:125], v[20:21]
	v_pk_fma_f32 v[36:37], v[126:127], v[126:127], v[36:37]
	v_pk_fma_f32 v[20:21], v[132:133], v[132:133], v[20:21]
	v_pk_fma_f32 v[36:37], v[134:135], v[134:135], v[36:37]
	v_pk_fma_f32 v[20:21], v[136:137], v[136:137], v[20:21]
	v_pk_fma_f32 v[36:37], v[138:139], v[138:139], v[36:37]
	v_pk_fma_f32 v[20:21], v[140:141], v[140:141], v[20:21]
	v_pk_fma_f32 v[36:37], v[142:143], v[142:143], v[36:37]
	v_pk_add_f32 v[20:21], v[20:21], v[36:37]
	s_nop 0
	v_add_f32_e32 v11, v20, v21
	ds_bpermute_b32 v43, v5, v11
	s_waitcnt lgkmcnt(0)
	v_add_f32_e32 v11, v11, v43
	ds_bpermute_b32 v43, v6, v11
	s_waitcnt lgkmcnt(0)
	v_add_f32_e32 v11, v11, v43
	ds_bpermute_b32 v43, v7, v11
	s_waitcnt lgkmcnt(0)
	v_add_f32_e32 v11, v11, v43
	ds_bpermute_b32 v43, v8, v11
	s_waitcnt lgkmcnt(0)
	v_add_f32_e32 v11, v11, v43
	ds_bpermute_b32 v43, v9, v11
	s_waitcnt lgkmcnt(0)
	v_add_f32_e32 v11, v11, v43
	ds_bpermute_b32 v43, v10, v11
	s_waitcnt lgkmcnt(0)
	v_add_f32_e32 v11, v11, v43
	v_fmamk_f32 v11, v11, 0x3a000000, v3
	v_mul_f32_e32 v129, 0x4f800000, v11
	v_cmp_gt_f32_e32 vcc, s85, v11
	s_nop 1
	v_cndmask_b32_e32 v11, v11, v129, vcc
	v_sqrt_f32_e32 v129, v11
	s_nop 0
	v_add_u32_e32 v156, -1, v129
	v_add_u32_e32 v157, 1, v129
	v_fma_f32 v158, -v156, v129, v11
	v_fma_f32 v43, -v157, v129, v11
	v_cmp_ge_f32_e64 s[80:81], 0, v158
	s_nop 1
	v_cndmask_b32_e64 v129, v129, v156, s[80:81]
	v_cmp_lt_f32_e64 s[80:81], 0, v43
	s_nop 1
	v_cndmask_b32_e64 v129, v129, v157, s[80:81]
	v_mul_f32_e32 v156, 0x37800000, v129
	v_cndmask_b32_e32 v129, v129, v156, vcc
	v_cmp_class_f32_e32 vcc, v11, v4
	s_nop 1
	v_cndmask_b32_e32 v11, v129, v11, vcc
	v_div_scale_f32 v129, s[80:81], v11, v11, 1.0
	v_rcp_f32_e32 v157, v129
	v_div_scale_f32 v156, vcc, 1.0, v11, 1.0
	v_fma_f32 v158, -v129, v157, 1.0
	v_fmac_f32_e32 v157, v158, v157
	v_mul_f32_e32 v158, v156, v157
	v_fma_f32 v43, -v129, v158, v156
	v_fmac_f32_e32 v158, v43, v157
	v_fma_f32 v129, -v129, v158, v156
	v_div_fmas_f32 v129, v129, v157, v158
	v_div_fixup_f32 v130, v129, v11, 1.0
	v_pk_mul_f32 v[144:145], v[88:89], v[130:131] op_sel_hi:[1,0]
	v_pk_mul_f32 v[146:147], v[90:91], v[130:131] op_sel_hi:[1,0]
	v_pk_mul_f32 v[144:145], v[12:13], v[144:145]
	v_pk_mul_f32 v[146:147], v[14:15], v[146:147]
	v_cvt_pk_bf16_f32 v148, v144, v145
	v_cvt_pk_bf16_f32 v149, v146, v147
	global_store_dwordx2 v1, v[148:149], s[78:79] offset:0
	v_pk_mul_f32 v[144:145], v[112:113], v[130:131] op_sel_hi:[1,0]
	v_pk_mul_f32 v[146:147], v[114:115], v[130:131] op_sel_hi:[1,0]
	v_pk_mul_f32 v[144:145], v[16:17], v[144:145]
	v_pk_mul_f32 v[146:147], v[18:19], v[146:147]
	v_cvt_pk_bf16_f32 v150, v144, v145
	v_cvt_pk_bf16_f32 v151, v146, v147
	global_store_dwordx2 v1, v[150:151], s[78:79] offset:512
	v_pk_mul_f32 v[144:145], v[116:117], v[130:131] op_sel_hi:[1,0]
	v_pk_mul_f32 v[146:147], v[118:119], v[130:131] op_sel_hi:[1,0]
	v_pk_mul_f32 v[144:145], v[24:25], v[144:145]
	v_pk_mul_f32 v[146:147], v[26:27], v[146:147]
	v_cvt_pk_bf16_f32 v152, v144, v145
	v_cvt_pk_bf16_f32 v153, v146, v147
	global_store_dwordx2 v1, v[152:153], s[78:79] offset:1024
	v_pk_mul_f32 v[144:145], v[120:121], v[130:131] op_sel_hi:[1,0]
	v_pk_mul_f32 v[146:147], v[122:123], v[130:131] op_sel_hi:[1,0]
	v_pk_mul_f32 v[144:145], v[28:29], v[144:145]
	v_pk_mul_f32 v[146:147], v[30:31], v[146:147]
	v_cvt_pk_bf16_f32 v154, v144, v145
	v_cvt_pk_bf16_f32 v155, v146, v147
	global_store_dwordx2 v1, v[154:155], s[78:79] offset:1536
	v_pk_mul_f32 v[144:145], v[124:125], v[130:131] op_sel_hi:[1,0]
	v_pk_mul_f32 v[146:147], v[126:127], v[130:131] op_sel_hi:[1,0]
	v_pk_mul_f32 v[144:145], v[32:33], v[144:145]
	v_pk_mul_f32 v[146:147], v[34:35], v[146:147]
	v_cvt_pk_bf16_f32 v148, v144, v145
	v_cvt_pk_bf16_f32 v149, v146, v147
	global_store_dwordx2 v1, v[148:149], s[78:79] offset:2048
	v_pk_mul_f32 v[144:145], v[132:133], v[130:131] op_sel_hi:[1,0]
	v_pk_mul_f32 v[146:147], v[134:135], v[130:131] op_sel_hi:[1,0]
	v_pk_mul_f32 v[144:145], v[44:45], v[144:145]
	v_pk_mul_f32 v[146:147], v[46:47], v[146:147]
	v_cvt_pk_bf16_f32 v150, v144, v145
	v_cvt_pk_bf16_f32 v151, v146, v147
	global_store_dwordx2 v1, v[150:151], s[78:79] offset:2560
	v_pk_mul_f32 v[144:145], v[136:137], v[130:131] op_sel_hi:[1,0]
	v_pk_mul_f32 v[146:147], v[138:139], v[130:131] op_sel_hi:[1,0]
	v_pk_mul_f32 v[144:145], v[48:49], v[144:145]
	v_pk_mul_f32 v[146:147], v[50:51], v[146:147]
	v_cvt_pk_bf16_f32 v152, v144, v145
	v_cvt_pk_bf16_f32 v153, v146, v147
	global_store_dwordx2 v1, v[152:153], s[78:79] offset:3072
	v_pk_mul_f32 v[144:145], v[140:141], v[130:131] op_sel_hi:[1,0]
	v_pk_mul_f32 v[146:147], v[142:143], v[130:131] op_sel_hi:[1,0]
	v_pk_mul_f32 v[144:145], v[52:53], v[144:145]
	v_pk_mul_f32 v[146:147], v[54:55], v[146:147]
	v_cvt_pk_bf16_f32 v154, v144, v145
	v_cvt_pk_bf16_f32 v155, v146, v147
	global_store_dwordx2 v1, v[154:155], s[78:79] offset:3584
	s_add_u32 s78, s78, s62
	s_addc_u32 s79, s79, 0
	s_mov_b32 s20, s84
	s_cmp_lt_u32 s20, 0x800
	s_cbranch_scc1 .Lrow_prom_top
.Lrow_prom_done:
	s_waitcnt vmcnt(0)
.LBB0_54:
	v_lshrrev_b32_e32 v1, 20, v0
	v_lshrrev_b32_e32 v0, 10, v0
	v_or_b32_e32 v0, v0, v1
	s_movk_i32 s0, 0x3ff
	v_and_or_b32 v0, v0, s0, v162
	v_cmp_eq_u32_e32 vcc, 0, v0
	s_barrier
	s_and_saveexec_b64 s[0:1], vcc
	s_cbranch_execz .LBB0_64
	buffer_wbl2 sc1
	s_waitcnt vmcnt(0)
	s_load_dwordx2 s[4:5], s[6:7], 0x58
	v_mov_b32_e32 v2, 0
	s_mov_b64 s[12:13], exec
	v_mbcnt_lo_u32_b32 v1, s12, 0
	v_mbcnt_hi_u32_b32 v1, s13, v1
	s_waitcnt lgkmcnt(0)
	global_load_dword v0, v2, s[4:5] offset:40
	v_cmp_eq_u32_e32 vcc, 0, v1
	s_and_saveexec_b64 s[6:7], vcc
	s_cbranch_execz .LBB0_57
	s_bcnt1_i32_b64 s3, s[12:13]
	v_mov_b32_e32 v3, s3
	global_atomic_add v3, v2, v3, s[4:5] offset:32 sc0
